# norm rows: regular rows XCD-local (row blocks 8x..8x+7 on XCD x), split-K tail rows still spread 2 per CU
# speedup vs baseline: 1.0088x; 1.0044x over previous
; DI void norm_phase(const float* xp, const float* xs, const float* gvec, const float* MODL  , int sc_off, bf16_t* H, int tid,
;                    const float* P, int nparts, const float* pgate, float* X) {
;     const int lane = tid & 63, gw = blockIdx.x * 8 + (tid >> 6), NGW = gridDim.x * 8;
;     for (int it = gw; it < M; it += NGW) {
;         const int row = it < MS ? MP + it : it - MS;
;         const int bi = batch_of(row);
;         const float* xr = (row < MP ? xp : xs) + (size_t)row * 1024; const float* mr = MODL + (size_t)bi * NMOD;
.LBB0_11:
	s_mov_b64 s[34:35], s[78:79]
	s_mov_b32 s38, s76
	s_mov_b32 s51, s82
	v_mbcnt_lo_u32_b32 v0, -1, 0
	v_mbcnt_hi_u32_b32 v0, -1, v0
	s_mov_b64 s[4:5], -1
	v_add_u32_e32 v194, s90, v0
	s_load_dwordx4 s[24:27], s[34:35], 0x108
	s_mov_b64 s[0:1], 0
	s_mov_b64 s[2:3], 0
	s_waitcnt lgkmcnt(0)
	s_add_u32 s36, s26, 0x7f00000
	s_addc_u32 s37, s27, 0
	s_cmp_lt_i32 s86, 1
	s_cbranch_scc1 .LBB0_19
	s_cmp_gt_i32 s86, 37
	s_cbranch_scc0 .LBB0_132
	s_cmp_eq_u32 s86, 38
	s_mov_b64 s[2:3], -1
	s_cbranch_scc0 .LBB0_131
	v_ashrrev_i32_e32 v0, 6, v194
	v_add_u32_e32 v20, s83, v0
	s_mov_b32 s101, s48
	s_cmpk_lg_i32 s51, 0x100
	s_cbranch_scc1 .Lni_a
	s_bfe_u32 s101, s83, 0x30003
	s_lshl_b32 s101, s101, 11
	s_lshr_b32 s2, s83, 6
	s_add_i32 s2, s2, s101
	s_addk_i32 s2, 0x200
	v_lshl_add_u32 v110, v0, 5, s2
	s_lshr_b32 s2, s83, 3
	v_lshl_add_u32 v20, v0, 8, s2
	v_cmp_gt_u32_e32 vcc, 2, v0
	s_nop 1
	v_cndmask_b32_e32 v20, v110, v20, vcc
	s_movk_i32 s101, 0x100

; __device__ __forceinline__ void st_bf4(bf16_t* p, const f32x4 v) { u32x2 w; w.x = cvt_pk_bf16(v[0], v[1]); w.y = cvt_pk_bf16(v[2], v[3]); *(u32x2*)p = w; }
; DI void norm_phase(const float* xp, const float* xs, const float* gvec, const float* MODL  , int sc_off, bf16_t* H, int tid,
;                    const float* P, int nparts, const float* pgate, float* X) {
;     ...
;     for (int it = gw; it < M; it += NGW) {
;         const int row = it < MS ? MP + it : it - MS;
;         const int bi = batch_of(row);
;         const float* xr = (row < MP ? xp : xs) + (size_t)row * 1024; const float* mr = MODL + (size_t)bi * NMOD;
;         f32x4 v[4]; float ss = 0.f;
; #pragma unroll
;         for (int j = 0; j < 4; ++j) v[j] = *(const f32x4*)(xr + 4 * lane + 256 * j);
;         if (row >= MP && nparts > 0) {
;             f32x4 s[4];
; #pragma unroll
;             for (int j = 0; j < 4; ++j) s[j] = (f32x4){0.f, 0.f, 0.f, 0.f};
;             for (int p = 0; p < nparts; ++p) { const float* pr = P + ((size_t)p * 512 + (row - MP)) * 1024 + 4 * lane;
; #pragma unroll
;                 for (int j = 0; j < 4; ++j) s[j] += *(const f32x4*)(pr + 256 * j); }
; #pragma unroll
;             for (int j = 0; j < 4; ++j) { v[j] += *(const f32x4*)(pgate + (size_t)bi * NMOD + 4 * lane + 256 * j) * s[j]; *(f32x4*)(X + (size_t)row * 1024 + 4 * lane + 256 * j) = v[j]; }
;         }
; #pragma unroll
;         for (int j = 0; j < 4; ++j) ss += v[j][0] * v[j][0] + v[j][1] * v[j][1] + v[j][2] * v[j][2] + v[j][3] * v[j][3];
;         const float r = rsqrtf(wave_sum(ss, lane) * (1.f / 1024.f) + 1e-6f);
;         if (H) {
; #pragma unroll
;             for (int j = 0; j < 4; ++j) { const int c = 4 * lane + 256 * j; const f32x4 g = *(const f32x4*)(gvec + c), sh = *(const f32x4*)(mr + c), sc = *(const f32x4*)(mr + sc_off + c);
;                 st_bf4(H + (size_t)row * 1024 + c, v[j] * r * g * (1.f + sc) + sh); }
;         } else {
; #pragma unroll
;             for (int j = 0; j < 4; ++j) { const int c = 4 * lane + 256 * j; *(f32x4*)(X + (size_t)row * 1024 + c) = v[j] * r * *(const f32x4*)(gvec + c); }
;         }
;     }
.LBB0_16:
	s_or_b64 exec, exec, s[6:7]
	s_waitcnt vmcnt(0)
	v_pk_mul_f32 v[40:41], v[12:13], v[12:13]
	s_waitcnt vmcnt(2)
	v_pk_mul_f32 v[42:43], v[8:9], v[8:9]
	v_pk_mul_f32 v[36:37], v[14:15], v[14:15]
	v_pk_mul_f32 v[38:39], v[10:11], v[10:11]
	v_mov_b32_e32 v44, v40
	v_mov_b32_e32 v45, v42
	v_mov_b32_e32 v42, v41
	v_pk_add_f32 v[40:41], v[44:45], v[42:43]
	v_mov_b32_e32 v42, v36
	v_mov_b32_e32 v43, v38
	s_waitcnt vmcnt(0)
	v_pk_mul_f32 v[32:33], v[0:1], v[0:1]
	v_pk_mul_f32 v[34:35], v[4:5], v[4:5]
	v_pk_add_f32 v[40:41], v[42:43], v[40:41]
	v_mov_b32_e32 v38, v37
	v_pk_mul_f32 v[16:17], v[2:3], v[2:3]
	v_pk_mul_f32 v[18:19], v[6:7], v[6:7]
	v_pk_add_f32 v[36:37], v[38:39], v[40:41]
	v_mov_b32_e32 v38, v32
	v_mov_b32_e32 v39, v34
	v_mov_b32_e32 v34, v33
	v_pk_add_f32 v[32:33], v[38:39], v[34:35]
	v_mov_b32_e32 v34, v16
	v_mov_b32_e32 v35, v18
	v_pk_add_f32 v[32:33], v[34:35], v[32:33]
	v_mov_b32_e32 v18, v17
	v_pk_add_f32 v[16:17], v[18:19], v[32:33]
	global_load_dwordx4 v[32:35], v[28:29], off
	global_load_dwordx4 v[198:201], v[28:29], off offset:1024
	global_load_dwordx4 v[202:205], v[28:29], off offset:2048
	global_load_dwordx4 v[206:209], v[28:29], off offset:3072
	v_add_f32_e32 v18, v36, v37
	v_add_f32_e32 v17, v17, v18
	v_add_f32_e32 v16, v16, v17
	ds_bpermute_b32 v17, v50, v16
	s_cmpk_eq_i32 s82, 0x100
	s_cselect_b32 s6, 0x200, 0
	v_cmp_gt_i32_e64 s[6:7], s6, v20
	v_add_u32_e32 v20, s101, v20
	s_nop 0
	v_cndmask_b32_e64 v20, v20, v110, s[6:7]
	s_bfe_u32 s6, s83, 0x30003
	s_lshl_b32 s6, s6, 11
	s_addk_i32 s6, 0x9ff
	s_cmpk_eq_i32 s82, 0x100
	s_cselect_b32 s6, s6, 0x41ff
	s_waitcnt lgkmcnt(0)
	v_add_f32_e32 v16, v16, v17
	ds_bpermute_b32 v17, v51, v16
	s_waitcnt lgkmcnt(0)
	v_add_f32_e32 v16, v16, v17
	ds_bpermute_b32 v17, v52, v16
	s_waitcnt lgkmcnt(0)
	v_add_f32_e32 v16, v16, v17
	ds_bpermute_b32 v17, v53, v16
	s_waitcnt lgkmcnt(0)
	v_add_f32_e32 v16, v16, v17
	ds_bpermute_b32 v17, v54, v16
	s_waitcnt lgkmcnt(0)
	v_add_f32_e32 v16, v16, v17
	ds_bpermute_b32 v17, v55, v16
	s_waitcnt lgkmcnt(0)
	v_add_f32_e32 v16, v16, v17
	v_mov_b32_e32 v17, 0x358637bd
	v_fmamk_f32 v16, v16, 0x3a800000, v17
	v_cmp_gt_f32_e32 vcc, s42, v16
	v_mul_f32_e32 v17, 0x4b800000, v16
	s_nop 0
	v_cndmask_b32_e32 v16, v16, v17, vcc
	v_rsq_f32_e32 v16, v16
	s_nop 0
	v_mul_f32_e32 v17, 0x45800000, v16
	v_cndmask_b32_e32 v16, v16, v17, vcc
	v_pk_mul_f32 v[12:13], v[12:13], v[16:17] op_sel_hi:[1,0]
	v_pk_mul_f32 v[14:15], v[14:15], v[16:17] op_sel_hi:[1,0]
	v_cmp_lt_i32_e32 vcc, s6, v20
	s_or_b64 s[4:5], vcc, s[4:5]
	s_waitcnt vmcnt(3)
	v_pk_mul_f32 v[14:15], v[34:35], v[14:15]
	v_pk_mul_f32 v[12:13], v[32:33], v[12:13]
	global_store_dwordx4 v[30:31], v[12:15], off
	v_pk_mul_f32 v[8:9], v[8:9], v[16:17] op_sel_hi:[1,0]
	v_pk_mul_f32 v[10:11], v[10:11], v[16:17] op_sel_hi:[1,0]
	s_waitcnt vmcnt(3)
	v_pk_mul_f32 v[8:9], v[198:199], v[8:9]
	v_pk_mul_f32 v[10:11], v[200:201], v[10:11]
	global_store_dwordx4 v[30:31], v[8:11], off offset:1024
	v_pk_mul_f32 v[4:5], v[4:5], v[16:17] op_sel_hi:[1,0]
	v_pk_mul_f32 v[6:7], v[6:7], v[16:17] op_sel_hi:[1,0]
	s_waitcnt vmcnt(3)
	v_pk_mul_f32 v[4:5], v[202:203], v[4:5]
	v_pk_mul_f32 v[6:7], v[204:205], v[6:7]
	global_store_dwordx4 v[30:31], v[4:7], off offset:2048
	v_pk_mul_f32 v[0:1], v[0:1], v[16:17] op_sel_hi:[1,0]
	v_pk_mul_f32 v[2:3], v[2:3], v[16:17] op_sel_hi:[1,0]
	s_waitcnt vmcnt(3)
	v_pk_mul_f32 v[0:1], v[206:207], v[0:1]
	v_pk_mul_f32 v[2:3], v[208:209], v[2:3]
	global_store_dwordx4 v[30:31], v[0:3], off offset:3072
	s_andn2_b64 exec, exec, s[4:5]
	s_cbranch_execz .LBB0_130

; DI void norm_phase(const float* xp, const float* xs, const float* gvec, const float* MODL  , int sc_off, bf16_t* H, int tid,
;                    const float* P, int nparts, const float* pgate, float* X) {
;     const int lane = tid & 63, gw = blockIdx.x * 8 + (tid >> 6), NGW = gridDim.x * 8;
;     for (int it = gw; it < M; it += NGW) {
;         const int row = it < MS ? MP + it : it - MS;
;         const int bi = batch_of(row);
;         const float* xr = (row < MP ? xp : xs) + (size_t)row * 1024; const float* mr = MODL + (size_t)bi * NMOD;
.LBB0_225:
	v_ashrrev_i32_e32 v0, 6, v194
	v_add_u32_e32 v16, s83, v0
	s_mov_b32 s101, s48
	s_cmpk_lg_i32 s51, 0x100
	s_cbranch_scc1 .Lni_b
	s_bfe_u32 s101, s83, 0x30003
	s_lshl_b32 s101, s101, 11
	s_lshr_b32 s2, s83, 6
	s_add_i32 s2, s2, s101
	s_addk_i32 s2, 0x200
	v_lshl_add_u32 v110, v0, 5, s2
	s_lshr_b32 s2, s83, 3
	v_lshl_add_u32 v16, v0, 8, s2
	v_cmp_gt_u32_e32 vcc, 2, v0
	s_nop 1
	v_cndmask_b32_e32 v16, v110, v16, vcc
	s_movk_i32 s101, 0x100

; __device__ __forceinline__ void st_bf4(bf16_t* p, const f32x4 v) { u32x2 w; w.x = cvt_pk_bf16(v[0], v[1]); w.y = cvt_pk_bf16(v[2], v[3]); *(u32x2*)p = w; }
; DI void norm_phase(const float* xp, const float* xs, const float* gvec, const float* MODL  , int sc_off, bf16_t* H, int tid,
;                    const float* P, int nparts, const float* pgate, float* X) {
;     ...
;     for (int it = gw; it < M; it += NGW) {
;         const int row = it < MS ? MP + it : it - MS;
;         const int bi = batch_of(row);
;         const float* xr = (row < MP ? xp : xs) + (size_t)row * 1024; const float* mr = MODL + (size_t)bi * NMOD;
;         f32x4 v[4]; float ss = 0.f;
; #pragma unroll
;         for (int j = 0; j < 4; ++j) v[j] = *(const f32x4*)(xr + 4 * lane + 256 * j);
;         if (row >= MP && nparts > 0) {
;             f32x4 s[4];
; #pragma unroll
;             for (int j = 0; j < 4; ++j) s[j] = (f32x4){0.f, 0.f, 0.f, 0.f};
;             for (int p = 0; p < nparts; ++p) { const float* pr = P + ((size_t)p * 512 + (row - MP)) * 1024 + 4 * lane;
; #pragma unroll
;                 for (int j = 0; j < 4; ++j) s[j] += *(const f32x4*)(pr + 256 * j); }
; #pragma unroll
;             for (int j = 0; j < 4; ++j) { v[j] += *(const f32x4*)(pgate + (size_t)bi * NMOD + 4 * lane + 256 * j) * s[j]; *(f32x4*)(X + (size_t)row * 1024 + 4 * lane + 256 * j) = v[j]; }
;         }
; #pragma unroll
;         for (int j = 0; j < 4; ++j) ss += v[j][0] * v[j][0] + v[j][1] * v[j][1] + v[j][2] * v[j][2] + v[j][3] * v[j][3];
;         const float r = rsqrtf(wave_sum(ss, lane) * (1.f / 1024.f) + 1e-6f);
;         if (H) {
; #pragma unroll
;             for (int j = 0; j < 4; ++j) { const int c = 4 * lane + 256 * j; const f32x4 g = *(const f32x4*)(gvec + c), sh = *(const f32x4*)(mr + c), sc = *(const f32x4*)(mr + sc_off + c);
;                 st_bf4(H + (size_t)row * 1024 + c, v[j] * r * g * (1.f + sc) + sh); }
.LBB0_227:
	s_or_b64 exec, exec, s[6:7]
	s_waitcnt vmcnt(0)
	v_pk_mul_f32 v[50:51], v[12:13], v[12:13]
	v_pk_mul_f32 v[52:53], v[8:9], v[8:9]
	v_pk_mul_f32 v[46:47], v[14:15], v[14:15]
	v_pk_mul_f32 v[48:49], v[10:11], v[10:11]
	v_mov_b32_e32 v60, v50
	v_mov_b32_e32 v61, v52
	v_mov_b32_e32 v52, v51
	v_pk_add_f32 v[50:51], v[60:61], v[52:53]
	v_mov_b32_e32 v52, v46
	v_mov_b32_e32 v53, v48
	v_pk_mul_f32 v[42:43], v[0:1], v[0:1]
	v_pk_mul_f32 v[44:45], v[4:5], v[4:5]
	v_pk_add_f32 v[50:51], v[52:53], v[50:51]
	v_mov_b32_e32 v48, v47
	v_lshl_add_u64 v[40:41], v[36:37], 2, s[4:5]
	v_pk_mul_f32 v[36:37], v[2:3], v[2:3]
	v_pk_mul_f32 v[38:39], v[6:7], v[6:7]
	v_pk_add_f32 v[46:47], v[48:49], v[50:51]
	v_mov_b32_e32 v48, v42
	v_mov_b32_e32 v49, v44
	v_mov_b32_e32 v44, v43
	v_pk_add_f32 v[42:43], v[48:49], v[44:45]
	v_mov_b32_e32 v44, v36
	v_mov_b32_e32 v45, v38
	v_pk_add_f32 v[42:43], v[44:45], v[42:43]
	v_mov_b32_e32 v38, v37
	s_mov_b64 s[6:7], 0x1000
	v_pk_add_f32 v[36:37], v[38:39], v[42:43]
	v_lshl_add_u64 v[38:39], v[40:41], 0, s[6:7]
	v_lshl_add_u64 v[40:41], v[40:41], 0, v[96:97]
	v_lshl_add_u64 v[50:51], v[38:39], 0, v[96:97]
	v_add_f32_e32 v29, v46, v47
	global_load_dwordx4 v[42:45], v[24:25], off
	global_load_dwordx4 v[46:49], v[40:41], off
	v_add_f32_e32 v29, v37, v29
	global_load_dwordx4 v[50:53], v[50:51], off
	global_load_dwordx4 v[198:201], v[24:25], off offset:1024
	global_load_dwordx4 v[210:213], v[40:41], off offset:1024
	v_mov_b32_e32 v234, v28
	v_mov_b32_e32 v235, v97
	v_lshl_add_u64 v[234:235], v[38:39], 0, v[234:235]
	global_load_dwordx4 v[222:225], v[234:235], off
	global_load_dwordx4 v[202:205], v[24:25], off offset:2048
	global_load_dwordx4 v[214:217], v[40:41], off offset:2048
	v_mov_b32_e32 v236, v30
	v_mov_b32_e32 v237, v97
	v_lshl_add_u64 v[236:237], v[38:39], 0, v[236:237]
	global_load_dwordx4 v[226:229], v[236:237], off
	global_load_dwordx4 v[206:209], v[24:25], off offset:3072
	global_load_dwordx4 v[218:221], v[40:41], off offset:3072
	v_mov_b32_e32 v238, v32
	v_mov_b32_e32 v239, v97
	v_lshl_add_u64 v[238:239], v[38:39], 0, v[238:239]
	global_load_dwordx4 v[230:233], v[238:239], off
	v_add_f32_e32 v29, v36, v29
	ds_bpermute_b32 v31, v54, v29
	v_lshl_add_u64 v[34:35], v[34:35], 1, v[26:27]
	v_mov_b32_e32 v33, v97
	s_cmpk_eq_i32 s82, 0x100
	s_cselect_b32 s6, 0x200, 0
	v_cmp_gt_i32_e64 s[6:7], s6, v16
	v_add_u32_e32 v16, s101, v16
	s_nop 0
	v_cndmask_b32_e64 v16, v16, v110, s[6:7]
	s_bfe_u32 s6, s83, 0x30003
	s_lshl_b32 s6, s6, 11
	s_addk_i32 s6, 0x9ff
	s_cmpk_eq_i32 s82, 0x100
	s_cselect_b32 s6, s6, 0x41ff
	s_waitcnt lgkmcnt(0)
	v_add_f32_e32 v29, v29, v31
	ds_bpermute_b32 v31, v55, v29
	s_waitcnt lgkmcnt(0)
	v_add_f32_e32 v29, v29, v31
	ds_bpermute_b32 v31, v56, v29
	s_waitcnt lgkmcnt(0)
	v_add_f32_e32 v29, v29, v31
	ds_bpermute_b32 v31, v57, v29
	s_waitcnt lgkmcnt(0)
	v_add_f32_e32 v29, v29, v31
	ds_bpermute_b32 v31, v58, v29
	s_waitcnt lgkmcnt(0)
	v_add_f32_e32 v29, v29, v31
	ds_bpermute_b32 v31, v59, v29
	s_waitcnt lgkmcnt(0)
	v_add_f32_e32 v29, v29, v31
	v_mov_b32_e32 v31, 0x358637bd
	v_fmamk_f32 v29, v29, 0x3a800000, v31
	v_cmp_gt_f32_e32 vcc, s42, v29
	v_mul_f32_e32 v31, 0x4b800000, v29
	s_nop 0
	v_cndmask_b32_e32 v29, v29, v31, vcc
	v_rsq_f32_e32 v29, v29
	s_nop 0
	v_mul_f32_e32 v31, 0x45800000, v29
	v_cndmask_b32_e32 v36, v29, v31, vcc
	v_pk_mul_f32 v[14:15], v[14:15], v[36:37] op_sel_hi:[1,0]
	v_pk_mul_f32 v[12:13], v[12:13], v[36:37] op_sel_hi:[1,0]
	v_mov_b32_e32 v29, v97
	v_pk_mul_f32 v[10:11], v[10:11], v[36:37] op_sel_hi:[1,0]
	v_pk_mul_f32 v[8:9], v[8:9], v[36:37] op_sel_hi:[1,0]
	v_mov_b32_e32 v31, v97
	v_pk_mul_f32 v[6:7], v[6:7], v[36:37] op_sel_hi:[1,0]
	v_pk_mul_f32 v[4:5], v[4:5], v[36:37] op_sel_hi:[1,0]
	v_pk_mul_f32 v[2:3], v[2:3], v[36:37] op_sel_hi:[1,0]
	v_pk_mul_f32 v[0:1], v[0:1], v[36:37] op_sel_hi:[1,0]
	v_cmp_lt_i32_e32 vcc, s6, v16
	s_or_b64 s[8:9], vcc, s[8:9]
	s_waitcnt vmcnt(9)
	v_pk_mul_f32 v[12:13], v[42:43], v[12:13]
	v_pk_mul_f32 v[14:15], v[44:45], v[14:15]
	v_pk_add_f32 v[50:51], v[50:51], 1.0 op_sel_hi:[1,0]
	v_pk_add_f32 v[52:53], v[52:53], 1.0 op_sel_hi:[1,0]
	v_pk_fma_f32 v[12:13], v[50:51], v[12:13], v[46:47]
	v_pk_fma_f32 v[14:15], v[52:53], v[14:15], v[48:49]
	v_cvt_pk_bf16_f32 v12, v12, v13
	v_cvt_pk_bf16_f32 v13, v14, v15
	global_store_dwordx2 v[34:35], v[12:13], off
	s_waitcnt vmcnt(7)
	v_pk_mul_f32 v[8:9], v[198:199], v[8:9]
	v_pk_mul_f32 v[10:11], v[200:201], v[10:11]
	v_pk_add_f32 v[222:223], v[222:223], 1.0 op_sel_hi:[1,0]
	v_pk_add_f32 v[224:225], v[224:225], 1.0 op_sel_hi:[1,0]
	v_pk_fma_f32 v[8:9], v[222:223], v[8:9], v[210:211]
	v_pk_fma_f32 v[10:11], v[224:225], v[10:11], v[212:213]
	v_cvt_pk_bf16_f32 v8, v8, v9
	v_cvt_pk_bf16_f32 v9, v10, v11
	global_store_dwordx2 v[34:35], v[8:9], off offset:512
	s_waitcnt vmcnt(5)
	v_pk_mul_f32 v[4:5], v[202:203], v[4:5]
	v_pk_mul_f32 v[6:7], v[204:205], v[6:7]
	v_pk_add_f32 v[226:227], v[226:227], 1.0 op_sel_hi:[1,0]
	v_pk_add_f32 v[228:229], v[228:229], 1.0 op_sel_hi:[1,0]
	v_pk_fma_f32 v[4:5], v[226:227], v[4:5], v[214:215]
	v_pk_fma_f32 v[6:7], v[228:229], v[6:7], v[216:217]
	v_cvt_pk_bf16_f32 v4, v4, v5
	v_cvt_pk_bf16_f32 v5, v6, v7
	global_store_dwordx2 v[34:35], v[4:5], off offset:1024
	s_waitcnt vmcnt(3)
	v_pk_mul_f32 v[0:1], v[206:207], v[0:1]
	v_pk_mul_f32 v[2:3], v[208:209], v[2:3]
	v_pk_add_f32 v[230:231], v[230:231], 1.0 op_sel_hi:[1,0]
	v_pk_add_f32 v[232:233], v[232:233], 1.0 op_sel_hi:[1,0]
	v_pk_fma_f32 v[0:1], v[230:231], v[0:1], v[218:219]
	v_pk_fma_f32 v[2:3], v[232:233], v[2:3], v[220:221]
	v_cvt_pk_bf16_f32 v0, v0, v1
	v_cvt_pk_bf16_f32 v1, v2, v3
	global_store_dwordx2 v[34:35], v[0:1], off offset:1536
	s_andn2_b64 exec, exec, s[8:9]
	s_cbranch_execz .LBB0_230

; DI void norm_phase(const float* xp, const float* xs, const float* gvec, const float* MODL  , int sc_off, bf16_t* H, int tid,
;                    const float* P, int nparts, const float* pgate, float* X) {
;     const int lane = tid & 63, gw = blockIdx.x * 8 + (tid >> 6), NGW = gridDim.x * 8;
;     for (int it = gw; it < M; it += NGW) {
;         const int row = it < MS ? MP + it : it - MS;
;         const int bi = batch_of(row);
;         const float* xr = (row < MP ? xp : xs) + (size_t)row * 1024; const float* mr = MODL + (size_t)bi * NMOD;
.LBB0_1949:
	s_and_b64 vcc, exec, s[0:1]
	s_cbranch_vccz .LBB0_1956
	v_ashrrev_i32_e32 v0, 6, v194
	v_add_u32_e32 v20, s83, v0
	s_mov_b32 s101, s48
	s_cmpk_lg_i32 s51, 0x100
	s_cbranch_scc1 .Lni_c
	s_bfe_u32 s101, s83, 0x30003
	s_lshl_b32 s101, s101, 11
	s_lshr_b32 s0, s83, 6
	s_add_i32 s0, s0, s101
	s_addk_i32 s0, 0x200
	v_lshl_add_u32 v110, v0, 5, s0
	s_lshr_b32 s0, s83, 3
	v_lshl_add_u32 v20, v0, 8, s0
	v_cmp_gt_u32_e32 vcc, 2, v0
	s_nop 1
	v_cndmask_b32_e32 v20, v110, v20, vcc
	s_movk_i32 s101, 0x100

; __device__ __forceinline__ void st_bf4(bf16_t* p, const f32x4 v) { u32x2 w; w.x = cvt_pk_bf16(v[0], v[1]); w.y = cvt_pk_bf16(v[2], v[3]); *(u32x2*)p = w; }
; DI void norm_phase(const float* xp, const float* xs, const float* gvec, const float* MODL  , int sc_off, bf16_t* H, int tid,
;                    const float* P, int nparts, const float* pgate, float* X) {
;     ...
;     for (int it = gw; it < M; it += NGW) {
;         const int row = it < MS ? MP + it : it - MS;
;         const int bi = batch_of(row);
;         const float* xr = (row < MP ? xp : xs) + (size_t)row * 1024; const float* mr = MODL + (size_t)bi * NMOD;
;         f32x4 v[4]; float ss = 0.f;
; #pragma unroll
;         for (int j = 0; j < 4; ++j) v[j] = *(const f32x4*)(xr + 4 * lane + 256 * j);
;         if (row >= MP && nparts > 0) {
;             f32x4 s[4];
; #pragma unroll
;             for (int j = 0; j < 4; ++j) s[j] = (f32x4){0.f, 0.f, 0.f, 0.f};
;             for (int p = 0; p < nparts; ++p) { const float* pr = P + ((size_t)p * 512 + (row - MP)) * 1024 + 4 * lane;
; #pragma unroll
;                 for (int j = 0; j < 4; ++j) s[j] += *(const f32x4*)(pr + 256 * j); }
; #pragma unroll
;             for (int j = 0; j < 4; ++j) { v[j] += *(const f32x4*)(pgate + (size_t)bi * NMOD + 4 * lane + 256 * j) * s[j]; *(f32x4*)(X + (size_t)row * 1024 + 4 * lane + 256 * j) = v[j]; }
;         }
; #pragma unroll
;         for (int j = 0; j < 4; ++j) ss += v[j][0] * v[j][0] + v[j][1] * v[j][1] + v[j][2] * v[j][2] + v[j][3] * v[j][3];
;         const float r = rsqrtf(wave_sum(ss, lane) * (1.f / 1024.f) + 1e-6f);
;         if (H) {
; #pragma unroll
;             for (int j = 0; j < 4; ++j) { const int c = 4 * lane + 256 * j; const f32x4 g = *(const f32x4*)(gvec + c), sh = *(const f32x4*)(mr + c), sc = *(const f32x4*)(mr + sc_off + c);
;                 st_bf4(H + (size_t)row * 1024 + c, v[j] * r * g * (1.f + sc) + sh); }
.LBB0_1952:
	s_or_b64 exec, exec, s[6:7]
	s_waitcnt vmcnt(0)
	v_pk_mul_f32 v[50:51], v[12:13], v[12:13]
	v_pk_mul_f32 v[52:53], v[8:9], v[8:9]
	v_pk_mul_f32 v[46:47], v[14:15], v[14:15]
	v_pk_mul_f32 v[48:49], v[10:11], v[10:11]
	v_mov_b32_e32 v54, v50
	v_mov_b32_e32 v55, v52
	v_mov_b32_e32 v52, v51
	v_pk_add_f32 v[50:51], v[54:55], v[52:53]
	v_mov_b32_e32 v52, v46
	v_mov_b32_e32 v53, v48
	v_pk_mul_f32 v[42:43], v[0:1], v[0:1]
	v_pk_mul_f32 v[44:45], v[4:5], v[4:5]
	v_pk_add_f32 v[50:51], v[52:53], v[50:51]
	v_mov_b32_e32 v48, v47
	v_pk_mul_f32 v[16:17], v[2:3], v[2:3]
	v_pk_mul_f32 v[18:19], v[6:7], v[6:7]
	v_pk_add_f32 v[46:47], v[48:49], v[50:51]
	v_mov_b32_e32 v48, v42
	v_mov_b32_e32 v49, v44
	v_mov_b32_e32 v44, v43
	v_pk_add_f32 v[42:43], v[48:49], v[44:45]
	v_mov_b32_e32 v44, v16
	v_mov_b32_e32 v45, v18
	v_pk_add_f32 v[42:43], v[44:45], v[42:43]
	v_mov_b32_e32 v18, v17
	v_lshl_add_u64 v[40:41], v[40:41], 2, s[2:3]
	v_pk_add_f32 v[16:17], v[18:19], v[42:43]
	v_add_f32_e32 v18, v46, v47
	s_mov_b64 s[6:7], 0x1000
	v_add_f32_e32 v17, v17, v18
	v_lshl_add_u64 v[18:19], v[40:41], 0, s[6:7]
	v_lshl_add_u64 v[40:41], v[40:41], 0, v[96:97]
	v_lshl_add_u64 v[50:51], v[18:19], 0, v[96:97]
	global_load_dwordx4 v[42:45], v[28:29], off
	global_load_dwordx4 v[46:49], v[40:41], off
	v_add_f32_e32 v16, v16, v17
	global_load_dwordx4 v[50:53], v[50:51], off
	global_load_dwordx4 v[198:201], v[28:29], off offset:1024
	global_load_dwordx4 v[210:213], v[40:41], off offset:1024
	v_mov_b32_e32 v234, v32
	v_mov_b32_e32 v235, v97
	v_lshl_add_u64 v[234:235], v[18:19], 0, v[234:235]
	global_load_dwordx4 v[222:225], v[234:235], off
	global_load_dwordx4 v[202:205], v[28:29], off offset:2048
	global_load_dwordx4 v[214:217], v[40:41], off offset:2048
	v_mov_b32_e32 v236, v34
	v_mov_b32_e32 v237, v97
	v_lshl_add_u64 v[236:237], v[18:19], 0, v[236:237]
	global_load_dwordx4 v[226:229], v[236:237], off
	global_load_dwordx4 v[206:209], v[28:29], off offset:3072
	global_load_dwordx4 v[218:221], v[40:41], off offset:3072
	v_mov_b32_e32 v238, v36
	v_mov_b32_e32 v239, v97
	v_lshl_add_u64 v[238:239], v[18:19], 0, v[238:239]
	global_load_dwordx4 v[230:233], v[238:239], off
	ds_bpermute_b32 v17, v62, v16
	v_lshl_add_u64 v[38:39], v[38:39], 1, v[30:31]
	v_mov_b32_e32 v33, v97
	v_mov_b32_e32 v35, v97
	v_mov_b32_e32 v37, v97
	s_waitcnt lgkmcnt(0)
	v_add_f32_e32 v16, v16, v17
	ds_bpermute_b32 v17, v63, v16
	s_cmpk_eq_i32 s82, 0x100
	s_cselect_b32 s6, 0x200, 0
	v_cmp_gt_i32_e64 s[6:7], s6, v20
	v_add_u32_e32 v20, s101, v20
	s_nop 0
	v_cndmask_b32_e64 v20, v20, v110, s[6:7]
	s_bfe_u32 s6, s83, 0x30003
	s_lshl_b32 s6, s6, 11
	s_addk_i32 s6, 0x9ff
	s_cmpk_eq_i32 s82, 0x100
	s_cselect_b32 s6, s6, 0x41ff
	s_waitcnt lgkmcnt(0)
	v_add_f32_e32 v16, v16, v17
	ds_bpermute_b32 v17, v64, v16
	s_waitcnt lgkmcnt(0)
	v_add_f32_e32 v16, v16, v17
	ds_bpermute_b32 v17, v65, v16
	s_waitcnt lgkmcnt(0)
	v_add_f32_e32 v16, v16, v17
	ds_bpermute_b32 v17, v66, v16
	s_waitcnt lgkmcnt(0)
	v_add_f32_e32 v16, v16, v17
	ds_bpermute_b32 v17, v67, v16
	s_waitcnt lgkmcnt(0)
	v_add_f32_e32 v16, v16, v17
	v_mov_b32_e32 v17, 0x358637bd
	v_fmamk_f32 v16, v16, 0x3a800000, v17
	v_cmp_gt_f32_e32 vcc, s42, v16
	v_mul_f32_e32 v17, 0x4b800000, v16
	s_nop 0
	v_cndmask_b32_e32 v16, v16, v17, vcc
	v_rsq_f32_e32 v16, v16
	s_nop 0
	v_mul_f32_e32 v17, 0x45800000, v16
	v_cndmask_b32_e32 v16, v16, v17, vcc
	v_pk_mul_f32 v[14:15], v[14:15], v[16:17] op_sel_hi:[1,0]
	v_pk_mul_f32 v[12:13], v[12:13], v[16:17] op_sel_hi:[1,0]
	v_pk_mul_f32 v[10:11], v[10:11], v[16:17] op_sel_hi:[1,0]
	v_pk_mul_f32 v[8:9], v[8:9], v[16:17] op_sel_hi:[1,0]
	v_pk_mul_f32 v[6:7], v[6:7], v[16:17] op_sel_hi:[1,0]
	v_pk_mul_f32 v[4:5], v[4:5], v[16:17] op_sel_hi:[1,0]
	v_pk_mul_f32 v[2:3], v[2:3], v[16:17] op_sel_hi:[1,0]
	v_pk_mul_f32 v[0:1], v[0:1], v[16:17] op_sel_hi:[1,0]
	v_cmp_lt_i32_e32 vcc, s6, v20
	s_or_b64 s[4:5], vcc, s[4:5]
	s_waitcnt vmcnt(9)
	v_pk_mul_f32 v[12:13], v[42:43], v[12:13]
	v_pk_mul_f32 v[14:15], v[44:45], v[14:15]
	v_pk_add_f32 v[50:51], v[50:51], 1.0 op_sel_hi:[1,0]
	v_pk_add_f32 v[52:53], v[52:53], 1.0 op_sel_hi:[1,0]
	v_pk_fma_f32 v[12:13], v[50:51], v[12:13], v[46:47]
	v_pk_fma_f32 v[14:15], v[52:53], v[14:15], v[48:49]
	v_cvt_pk_bf16_f32 v12, v12, v13
	v_cvt_pk_bf16_f32 v13, v14, v15
	global_store_dwordx2 v[38:39], v[12:13], off
	s_waitcnt vmcnt(7)
	v_pk_mul_f32 v[8:9], v[198:199], v[8:9]
	v_pk_mul_f32 v[10:11], v[200:201], v[10:11]
	v_pk_add_f32 v[222:223], v[222:223], 1.0 op_sel_hi:[1,0]
	v_pk_add_f32 v[224:225], v[224:225], 1.0 op_sel_hi:[1,0]
	v_pk_fma_f32 v[8:9], v[222:223], v[8:9], v[210:211]
	v_pk_fma_f32 v[10:11], v[224:225], v[10:11], v[212:213]
	v_cvt_pk_bf16_f32 v8, v8, v9
	v_cvt_pk_bf16_f32 v9, v10, v11
	global_store_dwordx2 v[38:39], v[8:9], off offset:512
	s_waitcnt vmcnt(5)
	v_pk_mul_f32 v[4:5], v[202:203], v[4:5]
	v_pk_mul_f32 v[6:7], v[204:205], v[6:7]
	v_pk_add_f32 v[226:227], v[226:227], 1.0 op_sel_hi:[1,0]
	v_pk_add_f32 v[228:229], v[228:229], 1.0 op_sel_hi:[1,0]
	v_pk_fma_f32 v[4:5], v[226:227], v[4:5], v[214:215]
	v_pk_fma_f32 v[6:7], v[228:229], v[6:7], v[216:217]
	v_cvt_pk_bf16_f32 v4, v4, v5
	v_cvt_pk_bf16_f32 v5, v6, v7
	global_store_dwordx2 v[38:39], v[4:5], off offset:1024
	s_waitcnt vmcnt(3)
	v_pk_mul_f32 v[0:1], v[206:207], v[0:1]
	v_pk_mul_f32 v[2:3], v[208:209], v[2:3]
	v_pk_add_f32 v[230:231], v[230:231], 1.0 op_sel_hi:[1,0]
	v_pk_add_f32 v[232:233], v[232:233], 1.0 op_sel_hi:[1,0]
	v_pk_fma_f32 v[0:1], v[230:231], v[0:1], v[218:219]
	v_pk_fma_f32 v[2:3], v[232:233], v[2:3], v[220:221]
	v_cvt_pk_bf16_f32 v0, v0, v1
	v_cvt_pk_bf16_f32 v1, v2, v3
	global_store_dwordx2 v[38:39], v[0:1], off offset:1536
	s_andn2_b64 exec, exec, s[4:5]
	s_cbranch_execz .LBB0_1955
